# phase B: the block's last main tile (gate section) stores write-through so less dirty L2 data remains at the grid barrier
# baseline (speedup 1.0000x reference)
; __device__ __forceinline__ u32x2 pack4(f32x4 v) { u32x2 r; r.x = cvt_pk(v[0], v[1]); r.y = cvt_pk(v[2], v[3]); return r; }
; __device__ __forceinline__ float silu_f(float x) { return x * __builtin_amdgcn_rcpf(1.f + __builtin_amdgcn_exp2f(-1.4426950409f * x)); }
; __device__ __forceinline__ float sigm_f(float x) { return __builtin_amdgcn_rcpf(1.f + __builtin_amdgcn_exp2f(-1.4426950409f * x)); }
; template <int SEC> __device__ __forceinline__ void epiB2(const Params& p, int row, int col32, f32x4 v0, f32x4 v1, int fq) {
;     ...
;   else { f32x4 o0 = {sigm_f(v0[0]), sigm_f(v0[1]), sigm_f(v0[2]), sigm_f(v0[3])}, o1 = {sigm_f(v1[0]), sigm_f(v1[1]), sigm_f(v1[2]), sigm_f(v1[3])};
;     store_pair16((u16*)(ws + OFF_GATE) + (size_t)row * 3072 + (col32 - 4096), pack4(o0), pack4(o1), fq); }
; }
.LBB0_198:
	s_add_i32 s33, s33, s57
	s_cmpk_lt_u32 s52, 0x1000
	s_cselect_b32 s4, 3, 4
	s_cmpk_gt_u32 s52, 0xdff
	s_cselect_b32 s4, s4, 2
	s_cmpk_gt_u32 s52, 0x7ff
	s_cselect_b32 s4, s4, 1
	s_cmpk_gt_i32 s38, 0x3ff
	s_cselect_b32 s39, s4, 0
	s_cmp_lt_i32 s39, 2
	s_mov_b64 s[4:5], -1
	s_cbranch_scc1 .LBB0_216
	s_cmp_lt_i32 s39, 3
	s_cbranch_scc1 .LBB0_205
	s_cmp_lg_u32 s39, 3
	s_cbranch_scc0 .LBB0_202
	v_mbcnt_lo_u32_b32 v130, -1, 0
	v_mbcnt_hi_u32_b32 v130, -1, v130
	v_mul_f32_e32 v134, 0xbfb8aa3b, v127
	v_and_or_b32 v128, v130, 15, s33
	v_and_b32_e32 v131, 16, v130
	v_ashrrev_i32_e32 v130, 2, v130
	v_and_b32_e32 v130, -8, v130
	v_add_u32_e32 v132, v130, v131
	v_mul_f32_e32 v130, 0xbfb8aa3b, v124
	v_exp_f32_e32 v130, v130
	v_mul_f32_e32 v131, 0xbfb8aa3b, v125
	v_exp_f32_e32 v131, v131
	v_exp_f32_e32 v134, v134
	v_add_f32_e32 v130, 1.0, v130
	v_rcp_f32_e32 v137, v130
	v_add_f32_e32 v130, 1.0, v131
	v_mul_f32_e32 v131, 0xbfb8aa3b, v126
	v_exp_f32_e32 v131, v131
	v_rcp_f32_e32 v138, v130
	s_or_b32 s4, s38, s66
	s_ashr_i32 s5, s4, 31
	v_add_f32_e32 v130, 1.0, v131
	v_mul_f32_e32 v131, 0xbfb8aa3b, v120
	v_rcp_f32_e32 v139, v130
	v_add_f32_e32 v130, 1.0, v134
	v_exp_f32_e32 v131, v131
	v_mul_f32_e32 v134, 0xbfb8aa3b, v121
	v_exp_f32_e32 v134, v134
	v_rcp_f32_e32 v140, v130
	v_add_f32_e32 v130, 1.0, v131
	v_mul_f32_e32 v131, 0xbfb8aa3b, v122
	v_rcp_f32_e32 v141, v130
	v_add_f32_e32 v130, 1.0, v134
	v_exp_f32_e32 v131, v131
	v_mul_f32_e32 v134, 0xbfb8aa3b, v123
	v_exp_f32_e32 v134, v134
	v_rcp_f32_e32 v142, v130
	v_add_f32_e32 v130, 1.0, v131
	v_rcp_f32_e32 v143, v130
	v_add_f32_e32 v130, 1.0, v134
	v_rcp_f32_e32 v144, v130
	v_mov_b64_e32 v[130:131], s[50:51]
	v_ashrrev_i32_e32 v133, 31, v132
	v_mad_u64_u32 v[134:135], s[40:41], v128, s71, v[130:131]
	s_lshl_b64 s[4:5], s[4:5], 1
	v_cvt_pk_bf16_f32 v139, v139, v140
	v_cvt_pk_bf16_f32 v140, v141, v142
	v_mul_f32_e32 v142, 0xbfb8aa3b, v117
	v_lshl_add_u64 v[134:135], v[134:135], 0, s[4:5]
	v_lshlrev_b64 v[132:133], 1, v[132:133]
	v_exp_f32_e32 v142, v142
	v_lshl_add_u64 v[134:135], v[134:135], 0, v[132:133]
	v_cvt_pk_bf16_f32 v138, v137, v138
	v_cvt_pk_bf16_f32 v141, v143, v144
	v_add_co_u32_e32 v134, vcc, s72, v134
	v_permlane16_swap_b32_e32 v138, v140
	v_permlane16_swap_b32_e32 v139, v141
	v_addc_co_u32_e32 v135, vcc, 0, v135, vcc
	v_mul_f32_e32 v137, 0xbfb8aa3b, v116
	s_andn2_b64 exec, exec, s[36:37]
	global_store_dwordx4 v[134:135], v[138:141], off
	s_mov_b64 exec, s[36:37]
	global_store_dwordx4 v[134:135], v[138:141], off sc1
	s_mov_b64 exec, -1
	v_mul_f32_e32 v143, 0xbfb8aa3b, v114
	v_mul_f32_e32 v144, 0xbfb8aa3b, v115
	v_add_f32_e32 v138, 1.0, v142
	v_mul_f32_e32 v139, 0xbfb8aa3b, v118
	v_mul_f32_e32 v140, 0xbfb8aa3b, v119
	v_mul_f32_e32 v141, 0xbfb8aa3b, v112
	v_mul_f32_e32 v142, 0xbfb8aa3b, v113
	v_exp_f32_e32 v137, v137
	v_exp_f32_e32 v139, v139
	v_exp_f32_e32 v140, v140
	v_exp_f32_e32 v141, v141
	v_exp_f32_e32 v142, v142
	v_exp_f32_e32 v143, v143
	v_exp_f32_e32 v144, v144
	v_add_f32_e32 v137, 1.0, v137
	v_add_f32_e32 v139, 1.0, v139
	v_add_f32_e32 v140, 1.0, v140
	v_add_f32_e32 v141, 1.0, v141
	v_add_f32_e32 v142, 1.0, v142
	v_add_f32_e32 v143, 1.0, v143
	v_add_f32_e32 v144, 1.0, v144
	v_rcp_f32_e32 v137, v137
	v_rcp_f32_e32 v138, v138
	v_rcp_f32_e32 v139, v139
	v_rcp_f32_e32 v140, v140
	v_rcp_f32_e32 v141, v141
	v_rcp_f32_e32 v142, v142
	v_rcp_f32_e32 v143, v143
	v_rcp_f32_e32 v144, v144
	v_cvt_pk_bf16_f32 v138, v137, v138
	v_cvt_pk_bf16_f32 v139, v139, v140
	v_cvt_pk_bf16_f32 v140, v141, v142
	v_cvt_pk_bf16_f32 v141, v143, v144
	s_nop 0
	v_permlane16_swap_b32_e32 v138, v140
	v_permlane16_swap_b32_e32 v139, v141
	s_andn2_b64 exec, exec, s[36:37]
	global_store_dwordx4 v[134:135], v[138:141], off offset:256
	s_mov_b64 exec, s[36:37]
	global_store_dwordx4 v[134:135], v[138:141], off offset:256 sc1
	s_mov_b64 exec, -1
	v_mul_f32_e32 v134, 0xbfb8aa3b, v108
	v_exp_f32_e32 v134, v134
	v_mul_f32_e32 v135, 0xbfb8aa3b, v109
	v_exp_f32_e32 v135, v135
	v_mul_f32_e32 v139, 0xbfb8aa3b, v111
	v_add_f32_e32 v134, 1.0, v134
	v_rcp_f32_e32 v138, v134
	v_add_f32_e32 v134, 1.0, v135
	v_mul_f32_e32 v135, 0xbfb8aa3b, v110
	v_exp_f32_e32 v135, v135
	v_exp_f32_e32 v139, v139
	v_rcp_f32_e32 v140, v134
	v_or_b32_e32 v137, 16, v128
	v_add_f32_e32 v134, 1.0, v135
	v_mul_f32_e32 v135, 0xbfb8aa3b, v104
	v_rcp_f32_e32 v141, v134
	v_add_f32_e32 v134, 1.0, v139
	v_exp_f32_e32 v135, v135
	v_mul_f32_e32 v139, 0xbfb8aa3b, v105
	v_exp_f32_e32 v139, v139
	v_rcp_f32_e32 v142, v134
	v_add_f32_e32 v134, 1.0, v135
	v_mul_f32_e32 v135, 0xbfb8aa3b, v106
	v_rcp_f32_e32 v143, v134
	v_add_f32_e32 v134, 1.0, v139
	v_exp_f32_e32 v135, v135
	v_mul_f32_e32 v139, 0xbfb8aa3b, v107
	v_exp_f32_e32 v139, v139
	v_rcp_f32_e32 v144, v134
	v_add_f32_e32 v134, 1.0, v135
	v_rcp_f32_e32 v145, v134
	v_add_f32_e32 v134, 1.0, v139
	v_rcp_f32_e32 v146, v134
	v_mad_u64_u32 v[134:135], s[40:41], v137, s71, v[130:131]
	v_cvt_pk_bf16_f32 v139, v141, v142
	v_mul_f32_e32 v142, 0xbfb8aa3b, v101
	v_lshl_add_u64 v[134:135], v[134:135], 0, s[4:5]
	v_exp_f32_e32 v142, v142
	v_lshl_add_u64 v[134:135], v[134:135], 0, v[132:133]
	v_cvt_pk_bf16_f32 v138, v138, v140
	v_cvt_pk_bf16_f32 v140, v143, v144
	v_cvt_pk_bf16_f32 v141, v145, v146
	v_add_co_u32_e32 v134, vcc, s72, v134
	v_permlane16_swap_b32_e32 v138, v140
	v_permlane16_swap_b32_e32 v139, v141
	v_addc_co_u32_e32 v135, vcc, 0, v135, vcc
	v_mul_f32_e32 v137, 0xbfb8aa3b, v100
	s_andn2_b64 exec, exec, s[36:37]
	global_store_dwordx4 v[134:135], v[138:141], off
	s_mov_b64 exec, s[36:37]
	global_store_dwordx4 v[134:135], v[138:141], off sc1
	s_mov_b64 exec, -1
	v_mul_f32_e32 v143, 0xbfb8aa3b, v98
; __device__ __forceinline__ u32x2 pack4(f32x4 v) { u32x2 r; r.x = cvt_pk(v[0], v[1]); r.y = cvt_pk(v[2], v[3]); return r; }
; __device__ __forceinline__ float silu_f(float x) { return x * __builtin_amdgcn_rcpf(1.f + __builtin_amdgcn_exp2f(-1.4426950409f * x)); }
; __device__ __forceinline__ float sigm_f(float x) { return __builtin_amdgcn_rcpf(1.f + __builtin_amdgcn_exp2f(-1.4426950409f * x)); }
; template <int SEC> __device__ __forceinline__ void epiB2(const Params& p, int row, int col32, f32x4 v0, f32x4 v1, int fq) {
;     ...
;   else { f32x4 o0 = {sigm_f(v0[0]), sigm_f(v0[1]), sigm_f(v0[2]), sigm_f(v0[3])}, o1 = {sigm_f(v1[0]), sigm_f(v1[1]), sigm_f(v1[2]), sigm_f(v1[3])};
;     store_pair16((u16*)(ws + OFF_GATE) + (size_t)row * 3072 + (col32 - 4096), pack4(o0), pack4(o1), fq); }
	v_mul_f32_e32 v144, 0xbfb8aa3b, v99
	v_add_f32_e32 v138, 1.0, v142
	v_mul_f32_e32 v139, 0xbfb8aa3b, v102
	v_mul_f32_e32 v140, 0xbfb8aa3b, v103
	v_mul_f32_e32 v141, 0xbfb8aa3b, v96
	v_mul_f32_e32 v142, 0xbfb8aa3b, v97
	v_exp_f32_e32 v137, v137
	v_exp_f32_e32 v139, v139
	v_exp_f32_e32 v140, v140
	v_exp_f32_e32 v141, v141
	v_exp_f32_e32 v142, v142
	v_exp_f32_e32 v143, v143
	v_exp_f32_e32 v144, v144
	v_add_f32_e32 v137, 1.0, v137
	v_add_f32_e32 v139, 1.0, v139
	v_add_f32_e32 v140, 1.0, v140
	v_add_f32_e32 v141, 1.0, v141
	v_add_f32_e32 v142, 1.0, v142
	v_add_f32_e32 v143, 1.0, v143
	v_add_f32_e32 v144, 1.0, v144
	v_rcp_f32_e32 v137, v137
	v_rcp_f32_e32 v138, v138
	v_rcp_f32_e32 v139, v139
	v_rcp_f32_e32 v140, v140
	v_rcp_f32_e32 v141, v141
	v_rcp_f32_e32 v142, v142
	v_rcp_f32_e32 v143, v143
	v_rcp_f32_e32 v144, v144
	v_cvt_pk_bf16_f32 v138, v137, v138
	v_cvt_pk_bf16_f32 v139, v139, v140
	v_cvt_pk_bf16_f32 v140, v141, v142
	v_cvt_pk_bf16_f32 v141, v143, v144
	s_nop 0
	v_permlane16_swap_b32_e32 v138, v140
	v_permlane16_swap_b32_e32 v139, v141
	s_andn2_b64 exec, exec, s[36:37]
	global_store_dwordx4 v[134:135], v[138:141], off offset:256
	s_mov_b64 exec, s[36:37]
	global_store_dwordx4 v[134:135], v[138:141], off offset:256 sc1
	s_mov_b64 exec, -1
	v_mul_f32_e32 v134, 0xbfb8aa3b, v92
	v_exp_f32_e32 v134, v134
	v_mul_f32_e32 v135, 0xbfb8aa3b, v93
	v_exp_f32_e32 v135, v135
	v_mul_f32_e32 v139, 0xbfb8aa3b, v95
	v_add_f32_e32 v134, 1.0, v134
	v_rcp_f32_e32 v138, v134
	v_add_f32_e32 v134, 1.0, v135
	v_mul_f32_e32 v135, 0xbfb8aa3b, v94
	v_exp_f32_e32 v135, v135
	v_exp_f32_e32 v139, v139
	v_rcp_f32_e32 v140, v134
	v_or_b32_e32 v137, 32, v128
	v_add_f32_e32 v134, 1.0, v135
	v_mul_f32_e32 v135, 0xbfb8aa3b, v88
	v_rcp_f32_e32 v141, v134
	v_add_f32_e32 v134, 1.0, v139
	v_exp_f32_e32 v135, v135
	v_mul_f32_e32 v139, 0xbfb8aa3b, v89
	v_exp_f32_e32 v139, v139
	v_rcp_f32_e32 v142, v134
	v_add_f32_e32 v134, 1.0, v135
	v_mul_f32_e32 v135, 0xbfb8aa3b, v90
	v_rcp_f32_e32 v143, v134
	v_add_f32_e32 v134, 1.0, v139
	v_exp_f32_e32 v135, v135
	v_mul_f32_e32 v139, 0xbfb8aa3b, v91
	v_exp_f32_e32 v139, v139
	v_rcp_f32_e32 v144, v134
	v_add_f32_e32 v134, 1.0, v135
	v_rcp_f32_e32 v145, v134
	v_add_f32_e32 v134, 1.0, v139
	v_rcp_f32_e32 v146, v134
	v_mad_u64_u32 v[134:135], s[40:41], v137, s71, v[130:131]
	v_cvt_pk_bf16_f32 v139, v141, v142
	v_mul_f32_e32 v142, 0xbfb8aa3b, v85
	v_lshl_add_u64 v[134:135], v[134:135], 0, s[4:5]
	v_exp_f32_e32 v142, v142
	v_lshl_add_u64 v[134:135], v[134:135], 0, v[132:133]
	v_cvt_pk_bf16_f32 v138, v138, v140
	v_cvt_pk_bf16_f32 v140, v143, v144
	v_cvt_pk_bf16_f32 v141, v145, v146
	v_add_co_u32_e32 v134, vcc, s72, v134
	v_permlane16_swap_b32_e32 v138, v140
	v_permlane16_swap_b32_e32 v139, v141
	v_addc_co_u32_e32 v135, vcc, 0, v135, vcc
	v_mul_f32_e32 v137, 0xbfb8aa3b, v84
	s_andn2_b64 exec, exec, s[36:37]
	global_store_dwordx4 v[134:135], v[138:141], off
	s_mov_b64 exec, s[36:37]
	global_store_dwordx4 v[134:135], v[138:141], off sc1
	s_mov_b64 exec, -1
	v_mul_f32_e32 v143, 0xbfb8aa3b, v82
	v_mul_f32_e32 v144, 0xbfb8aa3b, v83
	v_add_f32_e32 v138, 1.0, v142
	v_mul_f32_e32 v139, 0xbfb8aa3b, v86
	v_mul_f32_e32 v140, 0xbfb8aa3b, v87
	v_mul_f32_e32 v141, 0xbfb8aa3b, v80
	v_mul_f32_e32 v142, 0xbfb8aa3b, v81
	v_exp_f32_e32 v137, v137
	v_exp_f32_e32 v139, v139
	v_exp_f32_e32 v140, v140
	v_exp_f32_e32 v141, v141
	v_exp_f32_e32 v142, v142
	v_exp_f32_e32 v143, v143
	v_exp_f32_e32 v144, v144
	v_add_f32_e32 v137, 1.0, v137
	v_add_f32_e32 v139, 1.0, v139
	v_add_f32_e32 v140, 1.0, v140
	v_add_f32_e32 v141, 1.0, v141
	v_add_f32_e32 v142, 1.0, v142
	v_add_f32_e32 v143, 1.0, v143
	v_add_f32_e32 v144, 1.0, v144
	v_rcp_f32_e32 v137, v137
	v_rcp_f32_e32 v138, v138
	v_rcp_f32_e32 v139, v139
	v_rcp_f32_e32 v140, v140
	v_rcp_f32_e32 v141, v141
	v_rcp_f32_e32 v142, v142
	v_rcp_f32_e32 v143, v143
	v_rcp_f32_e32 v144, v144
	v_cvt_pk_bf16_f32 v138, v137, v138
	v_cvt_pk_bf16_f32 v139, v139, v140
	v_cvt_pk_bf16_f32 v140, v141, v142
	v_cvt_pk_bf16_f32 v141, v143, v144
	s_nop 0
	v_permlane16_swap_b32_e32 v138, v140
	v_permlane16_swap_b32_e32 v139, v141
	s_andn2_b64 exec, exec, s[36:37]
	global_store_dwordx4 v[134:135], v[138:141], off offset:256
	s_mov_b64 exec, s[36:37]
	global_store_dwordx4 v[134:135], v[138:141], off offset:256 sc1
	s_mov_b64 exec, -1
	v_mul_f32_e32 v134, 0xbfb8aa3b, v76
	v_exp_f32_e32 v134, v134
	v_mul_f32_e32 v135, 0xbfb8aa3b, v77
	v_exp_f32_e32 v135, v135
	v_mul_f32_e32 v139, 0xbfb8aa3b, v79
	v_add_f32_e32 v134, 1.0, v134
	v_rcp_f32_e32 v138, v134
	v_add_f32_e32 v134, 1.0, v135
	v_mul_f32_e32 v135, 0xbfb8aa3b, v78
	v_exp_f32_e32 v135, v135
	v_exp_f32_e32 v139, v139
	v_rcp_f32_e32 v140, v134
	v_or_b32_e32 v137, 48, v128
	v_add_f32_e32 v134, 1.0, v135
	v_mul_f32_e32 v135, 0xbfb8aa3b, v72
	v_rcp_f32_e32 v141, v134
	v_add_f32_e32 v134, 1.0, v139
	v_exp_f32_e32 v135, v135
	v_mul_f32_e32 v139, 0xbfb8aa3b, v73
	v_exp_f32_e32 v139, v139
	v_rcp_f32_e32 v142, v134
	v_add_f32_e32 v134, 1.0, v135
	v_mul_f32_e32 v135, 0xbfb8aa3b, v74
	v_rcp_f32_e32 v143, v134
	v_add_f32_e32 v134, 1.0, v139
	v_exp_f32_e32 v135, v135
	v_mul_f32_e32 v139, 0xbfb8aa3b, v75
	v_exp_f32_e32 v139, v139
	v_rcp_f32_e32 v144, v134
	v_add_f32_e32 v134, 1.0, v135
	v_rcp_f32_e32 v145, v134
	v_add_f32_e32 v134, 1.0, v139
	v_rcp_f32_e32 v146, v134
	v_mad_u64_u32 v[134:135], s[40:41], v137, s71, v[130:131]
	v_cvt_pk_bf16_f32 v139, v141, v142
	v_mul_f32_e32 v142, 0xbfb8aa3b, v69
	v_lshl_add_u64 v[134:135], v[134:135], 0, s[4:5]
	v_exp_f32_e32 v142, v142
	v_lshl_add_u64 v[134:135], v[134:135], 0, v[132:133]
	v_cvt_pk_bf16_f32 v138, v138, v140
	v_cvt_pk_bf16_f32 v140, v143, v144
	v_cvt_pk_bf16_f32 v141, v145, v146
; __device__ __forceinline__ u32x2 pack4(f32x4 v) { u32x2 r; r.x = cvt_pk(v[0], v[1]); r.y = cvt_pk(v[2], v[3]); return r; }
; __device__ __forceinline__ float silu_f(float x) { return x * __builtin_amdgcn_rcpf(1.f + __builtin_amdgcn_exp2f(-1.4426950409f * x)); }
; __device__ __forceinline__ float sigm_f(float x) { return __builtin_amdgcn_rcpf(1.f + __builtin_amdgcn_exp2f(-1.4426950409f * x)); }
; template <int SEC> __device__ __forceinline__ void epiB2(const Params& p, int row, int col32, f32x4 v0, f32x4 v1, int fq) {
;     ...
;   else { f32x4 o0 = {sigm_f(v0[0]), sigm_f(v0[1]), sigm_f(v0[2]), sigm_f(v0[3])}, o1 = {sigm_f(v1[0]), sigm_f(v1[1]), sigm_f(v1[2]), sigm_f(v1[3])};
;     store_pair16((u16*)(ws + OFF_GATE) + (size_t)row * 3072 + (col32 - 4096), pack4(o0), pack4(o1), fq); }
	v_add_co_u32_e32 v134, vcc, s72, v134
	v_permlane16_swap_b32_e32 v138, v140
	v_permlane16_swap_b32_e32 v139, v141
	v_addc_co_u32_e32 v135, vcc, 0, v135, vcc
	v_mul_f32_e32 v137, 0xbfb8aa3b, v68
	s_andn2_b64 exec, exec, s[36:37]
	global_store_dwordx4 v[134:135], v[138:141], off
	s_mov_b64 exec, s[36:37]
	global_store_dwordx4 v[134:135], v[138:141], off sc1
	s_mov_b64 exec, -1
	v_mul_f32_e32 v143, 0xbfb8aa3b, v66
	v_mul_f32_e32 v144, 0xbfb8aa3b, v67
	v_add_f32_e32 v138, 1.0, v142
	v_mul_f32_e32 v139, 0xbfb8aa3b, v70
	v_mul_f32_e32 v140, 0xbfb8aa3b, v71
	v_mul_f32_e32 v141, 0xbfb8aa3b, v64
	v_mul_f32_e32 v142, 0xbfb8aa3b, v65
	v_exp_f32_e32 v137, v137
	v_exp_f32_e32 v139, v139
	v_exp_f32_e32 v140, v140
	v_exp_f32_e32 v141, v141
	v_exp_f32_e32 v142, v142
	v_exp_f32_e32 v143, v143
	v_exp_f32_e32 v144, v144
	v_add_f32_e32 v137, 1.0, v137
	v_add_f32_e32 v139, 1.0, v139
	v_add_f32_e32 v140, 1.0, v140
	v_add_f32_e32 v141, 1.0, v141
	v_add_f32_e32 v142, 1.0, v142
	v_add_f32_e32 v143, 1.0, v143
	v_add_f32_e32 v144, 1.0, v144
	v_rcp_f32_e32 v137, v137
	v_rcp_f32_e32 v138, v138
	v_rcp_f32_e32 v139, v139
	v_rcp_f32_e32 v140, v140
	v_rcp_f32_e32 v141, v141
	v_rcp_f32_e32 v142, v142
	v_rcp_f32_e32 v143, v143
	v_rcp_f32_e32 v144, v144
	v_cvt_pk_bf16_f32 v138, v137, v138
	v_cvt_pk_bf16_f32 v139, v139, v140
	v_cvt_pk_bf16_f32 v140, v141, v142
	v_cvt_pk_bf16_f32 v141, v143, v144
	s_nop 0
	v_permlane16_swap_b32_e32 v138, v140
	v_permlane16_swap_b32_e32 v139, v141
	s_andn2_b64 exec, exec, s[36:37]
	global_store_dwordx4 v[134:135], v[138:141], off offset:256
	s_mov_b64 exec, s[36:37]
	global_store_dwordx4 v[134:135], v[138:141], off offset:256 sc1
	s_mov_b64 exec, -1
	v_mul_f32_e32 v134, 0xbfb8aa3b, v60
	v_exp_f32_e32 v134, v134
	v_mul_f32_e32 v135, 0xbfb8aa3b, v61
	v_exp_f32_e32 v135, v135
	v_mul_f32_e32 v139, 0xbfb8aa3b, v63
	v_add_f32_e32 v134, 1.0, v134
	v_rcp_f32_e32 v138, v134
	v_add_f32_e32 v134, 1.0, v135
	v_mul_f32_e32 v135, 0xbfb8aa3b, v62
	v_exp_f32_e32 v135, v135
	v_exp_f32_e32 v139, v139
	v_rcp_f32_e32 v140, v134
	v_add_u32_e32 v137, 0x80, v128
	v_add_f32_e32 v134, 1.0, v135
	v_mul_f32_e32 v135, 0xbfb8aa3b, v56
	v_rcp_f32_e32 v141, v134
	v_add_f32_e32 v134, 1.0, v139
	v_exp_f32_e32 v135, v135
	v_mul_f32_e32 v139, 0xbfb8aa3b, v57
	v_exp_f32_e32 v139, v139
	v_rcp_f32_e32 v142, v134
	v_add_f32_e32 v134, 1.0, v135
	v_mul_f32_e32 v135, 0xbfb8aa3b, v58
	v_rcp_f32_e32 v143, v134
	v_add_f32_e32 v134, 1.0, v139
	v_exp_f32_e32 v135, v135
	v_mul_f32_e32 v139, 0xbfb8aa3b, v59
	v_exp_f32_e32 v139, v139
	v_rcp_f32_e32 v144, v134
	v_add_f32_e32 v134, 1.0, v135
	v_rcp_f32_e32 v145, v134
	v_add_f32_e32 v134, 1.0, v139
	v_rcp_f32_e32 v146, v134
	v_mad_u64_u32 v[134:135], s[40:41], v137, s71, v[130:131]
	v_cvt_pk_bf16_f32 v139, v141, v142
	v_mul_f32_e32 v142, 0xbfb8aa3b, v53
	v_lshl_add_u64 v[134:135], v[134:135], 0, s[4:5]
	v_exp_f32_e32 v142, v142
	v_lshl_add_u64 v[134:135], v[134:135], 0, v[132:133]
	v_cvt_pk_bf16_f32 v138, v138, v140
	v_cvt_pk_bf16_f32 v140, v143, v144
	v_cvt_pk_bf16_f32 v141, v145, v146
	v_add_co_u32_e32 v134, vcc, s72, v134
	v_permlane16_swap_b32_e32 v138, v140
	v_permlane16_swap_b32_e32 v139, v141
	v_addc_co_u32_e32 v135, vcc, 0, v135, vcc
	v_mul_f32_e32 v137, 0xbfb8aa3b, v52
	s_andn2_b64 exec, exec, s[36:37]
	global_store_dwordx4 v[134:135], v[138:141], off
	s_mov_b64 exec, s[36:37]
	global_store_dwordx4 v[134:135], v[138:141], off sc1
	s_mov_b64 exec, -1
	v_mul_f32_e32 v143, 0xbfb8aa3b, v50
	v_mul_f32_e32 v144, 0xbfb8aa3b, v51
	v_add_f32_e32 v138, 1.0, v142
	v_mul_f32_e32 v139, 0xbfb8aa3b, v54
	v_mul_f32_e32 v140, 0xbfb8aa3b, v55
	v_mul_f32_e32 v141, 0xbfb8aa3b, v48
	v_mul_f32_e32 v142, 0xbfb8aa3b, v49
	v_exp_f32_e32 v137, v137
	v_exp_f32_e32 v139, v139
	v_exp_f32_e32 v140, v140
	v_exp_f32_e32 v141, v141
	v_exp_f32_e32 v142, v142
	v_exp_f32_e32 v143, v143
	v_exp_f32_e32 v144, v144
	v_add_f32_e32 v137, 1.0, v137
	v_add_f32_e32 v139, 1.0, v139
	v_add_f32_e32 v140, 1.0, v140
	v_add_f32_e32 v141, 1.0, v141
	v_add_f32_e32 v142, 1.0, v142
	v_add_f32_e32 v143, 1.0, v143
	v_add_f32_e32 v144, 1.0, v144
	v_rcp_f32_e32 v137, v137
	v_rcp_f32_e32 v138, v138
	v_rcp_f32_e32 v139, v139
	v_rcp_f32_e32 v140, v140
	v_rcp_f32_e32 v141, v141
	v_rcp_f32_e32 v142, v142
	v_rcp_f32_e32 v143, v143
	v_rcp_f32_e32 v144, v144
	v_cvt_pk_bf16_f32 v138, v137, v138
	v_cvt_pk_bf16_f32 v139, v139, v140
	v_cvt_pk_bf16_f32 v140, v141, v142
	v_cvt_pk_bf16_f32 v141, v143, v144
	s_nop 0
	v_permlane16_swap_b32_e32 v138, v140
	v_permlane16_swap_b32_e32 v139, v141
	s_andn2_b64 exec, exec, s[36:37]
	global_store_dwordx4 v[134:135], v[138:141], off offset:256
	s_mov_b64 exec, s[36:37]
	global_store_dwordx4 v[134:135], v[138:141], off offset:256 sc1
	s_mov_b64 exec, -1
	v_mul_f32_e32 v134, 0xbfb8aa3b, v44
	v_exp_f32_e32 v134, v134
	v_mul_f32_e32 v135, 0xbfb8aa3b, v45
	v_exp_f32_e32 v135, v135
	v_mul_f32_e32 v139, 0xbfb8aa3b, v47
	v_add_f32_e32 v134, 1.0, v134
	v_rcp_f32_e32 v138, v134
	v_add_f32_e32 v134, 1.0, v135
	v_mul_f32_e32 v135, 0xbfb8aa3b, v46
	v_exp_f32_e32 v135, v135
	v_exp_f32_e32 v139, v139
	v_rcp_f32_e32 v140, v134
	v_add_u32_e32 v137, 0x90, v128
	v_add_f32_e32 v134, 1.0, v135
	v_mul_f32_e32 v135, 0xbfb8aa3b, v40
	v_rcp_f32_e32 v141, v134
	v_add_f32_e32 v134, 1.0, v139
	v_exp_f32_e32 v135, v135
	v_mul_f32_e32 v139, 0xbfb8aa3b, v41
	v_exp_f32_e32 v139, v139
	v_rcp_f32_e32 v142, v134
	v_add_f32_e32 v134, 1.0, v135
	v_mul_f32_e32 v135, 0xbfb8aa3b, v42
	v_rcp_f32_e32 v143, v134
	v_add_f32_e32 v134, 1.0, v139
	v_exp_f32_e32 v135, v135
	v_mul_f32_e32 v139, 0xbfb8aa3b, v43
	v_exp_f32_e32 v139, v139
	v_rcp_f32_e32 v144, v134
	v_add_f32_e32 v134, 1.0, v135
	v_rcp_f32_e32 v145, v134
; __device__ __forceinline__ u32x2 pack4(f32x4 v) { u32x2 r; r.x = cvt_pk(v[0], v[1]); r.y = cvt_pk(v[2], v[3]); return r; }
; __device__ __forceinline__ float silu_f(float x) { return x * __builtin_amdgcn_rcpf(1.f + __builtin_amdgcn_exp2f(-1.4426950409f * x)); }
; __device__ __forceinline__ float sigm_f(float x) { return __builtin_amdgcn_rcpf(1.f + __builtin_amdgcn_exp2f(-1.4426950409f * x)); }
; template <int SEC> __device__ __forceinline__ void epiB2(const Params& p, int row, int col32, f32x4 v0, f32x4 v1, int fq) {
;     ...
;   else { f32x4 o0 = {sigm_f(v0[0]), sigm_f(v0[1]), sigm_f(v0[2]), sigm_f(v0[3])}, o1 = {sigm_f(v1[0]), sigm_f(v1[1]), sigm_f(v1[2]), sigm_f(v1[3])};
;     store_pair16((u16*)(ws + OFF_GATE) + (size_t)row * 3072 + (col32 - 4096), pack4(o0), pack4(o1), fq); }
	v_add_f32_e32 v134, 1.0, v139
	v_rcp_f32_e32 v146, v134
	v_mad_u64_u32 v[134:135], s[40:41], v137, s71, v[130:131]
	v_cvt_pk_bf16_f32 v139, v141, v142
	v_mul_f32_e32 v142, 0xbfb8aa3b, v37
	v_lshl_add_u64 v[134:135], v[134:135], 0, s[4:5]
	v_exp_f32_e32 v142, v142
	v_lshl_add_u64 v[134:135], v[134:135], 0, v[132:133]
	v_cvt_pk_bf16_f32 v138, v138, v140
	v_cvt_pk_bf16_f32 v140, v143, v144
	v_cvt_pk_bf16_f32 v141, v145, v146
	v_add_co_u32_e32 v134, vcc, s72, v134
	v_permlane16_swap_b32_e32 v138, v140
	v_permlane16_swap_b32_e32 v139, v141
	v_addc_co_u32_e32 v135, vcc, 0, v135, vcc
	v_mul_f32_e32 v137, 0xbfb8aa3b, v36
	s_andn2_b64 exec, exec, s[36:37]
	global_store_dwordx4 v[134:135], v[138:141], off
	s_mov_b64 exec, s[36:37]
	global_store_dwordx4 v[134:135], v[138:141], off sc1
	s_mov_b64 exec, -1
	v_mul_f32_e32 v143, 0xbfb8aa3b, v34
	v_mul_f32_e32 v144, 0xbfb8aa3b, v35
	v_add_f32_e32 v138, 1.0, v142
	v_mul_f32_e32 v139, 0xbfb8aa3b, v38
	v_mul_f32_e32 v140, 0xbfb8aa3b, v39
	v_mul_f32_e32 v141, 0xbfb8aa3b, v32
	v_mul_f32_e32 v142, 0xbfb8aa3b, v33
	v_exp_f32_e32 v137, v137
	v_exp_f32_e32 v139, v139
	v_exp_f32_e32 v140, v140
	v_exp_f32_e32 v141, v141
	v_exp_f32_e32 v142, v142
	v_exp_f32_e32 v143, v143
	v_exp_f32_e32 v144, v144
	v_add_f32_e32 v137, 1.0, v137
	v_add_f32_e32 v139, 1.0, v139
	v_add_f32_e32 v140, 1.0, v140
	v_add_f32_e32 v141, 1.0, v141
	v_add_f32_e32 v142, 1.0, v142
	v_add_f32_e32 v143, 1.0, v143
	v_add_f32_e32 v144, 1.0, v144
	v_rcp_f32_e32 v137, v137
	v_rcp_f32_e32 v138, v138
	v_rcp_f32_e32 v139, v139
	v_rcp_f32_e32 v140, v140
	v_rcp_f32_e32 v141, v141
	v_rcp_f32_e32 v142, v142
	v_rcp_f32_e32 v143, v143
	v_rcp_f32_e32 v144, v144
	v_cvt_pk_bf16_f32 v138, v137, v138
	v_cvt_pk_bf16_f32 v139, v139, v140
	v_cvt_pk_bf16_f32 v140, v141, v142
	v_cvt_pk_bf16_f32 v141, v143, v144
	s_nop 0
	v_permlane16_swap_b32_e32 v138, v140
	v_permlane16_swap_b32_e32 v139, v141
	s_andn2_b64 exec, exec, s[36:37]
	global_store_dwordx4 v[134:135], v[138:141], off offset:256
	s_mov_b64 exec, s[36:37]
	global_store_dwordx4 v[134:135], v[138:141], off offset:256 sc1
	s_mov_b64 exec, -1
	v_mul_f32_e32 v134, 0xbfb8aa3b, v28
	v_exp_f32_e32 v134, v134
	v_mul_f32_e32 v135, 0xbfb8aa3b, v29
	v_exp_f32_e32 v135, v135
	v_mul_f32_e32 v139, 0xbfb8aa3b, v31
	v_add_f32_e32 v134, 1.0, v134
	v_rcp_f32_e32 v138, v134
	v_add_f32_e32 v134, 1.0, v135
	v_mul_f32_e32 v135, 0xbfb8aa3b, v30
	v_exp_f32_e32 v135, v135
	v_exp_f32_e32 v139, v139
	v_rcp_f32_e32 v140, v134
	v_add_u32_e32 v137, 0xa0, v128
	v_add_f32_e32 v134, 1.0, v135
	v_mul_f32_e32 v135, 0xbfb8aa3b, v24
	v_rcp_f32_e32 v141, v134
	v_add_f32_e32 v134, 1.0, v139
	v_exp_f32_e32 v135, v135
	v_mul_f32_e32 v139, 0xbfb8aa3b, v25
	v_exp_f32_e32 v139, v139
	v_rcp_f32_e32 v142, v134
	v_add_f32_e32 v134, 1.0, v135
	v_mul_f32_e32 v135, 0xbfb8aa3b, v26
	v_rcp_f32_e32 v143, v134
	v_add_f32_e32 v134, 1.0, v139
	v_exp_f32_e32 v135, v135
	v_mul_f32_e32 v139, 0xbfb8aa3b, v27
	v_exp_f32_e32 v139, v139
	v_rcp_f32_e32 v144, v134
	v_add_f32_e32 v134, 1.0, v135
	v_rcp_f32_e32 v145, v134
	v_add_f32_e32 v134, 1.0, v139
	v_rcp_f32_e32 v146, v134
	v_mad_u64_u32 v[134:135], s[40:41], v137, s71, v[130:131]
	v_cvt_pk_bf16_f32 v139, v141, v142
	v_mul_f32_e32 v142, 0xbfb8aa3b, v21
	v_lshl_add_u64 v[134:135], v[134:135], 0, s[4:5]
	v_exp_f32_e32 v142, v142
	v_lshl_add_u64 v[134:135], v[134:135], 0, v[132:133]
	v_cvt_pk_bf16_f32 v138, v138, v140
	v_cvt_pk_bf16_f32 v140, v143, v144
	v_cvt_pk_bf16_f32 v141, v145, v146
	v_add_co_u32_e32 v134, vcc, s72, v134
	v_permlane16_swap_b32_e32 v138, v140
	v_permlane16_swap_b32_e32 v139, v141
	v_addc_co_u32_e32 v135, vcc, 0, v135, vcc
	v_mul_f32_e32 v137, 0xbfb8aa3b, v20
	s_andn2_b64 exec, exec, s[36:37]
	global_store_dwordx4 v[134:135], v[138:141], off
	s_mov_b64 exec, s[36:37]
	global_store_dwordx4 v[134:135], v[138:141], off sc1
	s_mov_b64 exec, -1
	v_mul_f32_e32 v143, 0xbfb8aa3b, v18
	v_mul_f32_e32 v144, 0xbfb8aa3b, v19
	v_add_f32_e32 v138, 1.0, v142
	v_mul_f32_e32 v139, 0xbfb8aa3b, v22
	v_mul_f32_e32 v140, 0xbfb8aa3b, v23
	v_mul_f32_e32 v141, 0xbfb8aa3b, v16
	v_mul_f32_e32 v142, 0xbfb8aa3b, v17
; __device__ __forceinline__ u32x2 pack4(f32x4 v) { u32x2 r; r.x = cvt_pk(v[0], v[1]); r.y = cvt_pk(v[2], v[3]); return r; }
; __device__ __forceinline__ float silu_f(float x) { return x * __builtin_amdgcn_rcpf(1.f + __builtin_amdgcn_exp2f(-1.4426950409f * x)); }
; __device__ __forceinline__ float sigm_f(float x) { return __builtin_amdgcn_rcpf(1.f + __builtin_amdgcn_exp2f(-1.4426950409f * x)); }
; template <int SEC> __device__ __forceinline__ void epiB2(const Params& p, int row, int col32, f32x4 v0, f32x4 v1, int fq) {
;     ...
;   else { f32x4 o0 = {sigm_f(v0[0]), sigm_f(v0[1]), sigm_f(v0[2]), sigm_f(v0[3])}, o1 = {sigm_f(v1[0]), sigm_f(v1[1]), sigm_f(v1[2]), sigm_f(v1[3])};
;     store_pair16((u16*)(ws + OFF_GATE) + (size_t)row * 3072 + (col32 - 4096), pack4(o0), pack4(o1), fq); }
	v_exp_f32_e32 v137, v137
	v_exp_f32_e32 v139, v139
	v_exp_f32_e32 v140, v140
	v_exp_f32_e32 v141, v141
	v_exp_f32_e32 v142, v142
	v_exp_f32_e32 v143, v143
	v_exp_f32_e32 v144, v144
	v_add_f32_e32 v137, 1.0, v137
	v_add_f32_e32 v139, 1.0, v139
	v_add_f32_e32 v140, 1.0, v140
	v_add_f32_e32 v141, 1.0, v141
	v_add_f32_e32 v142, 1.0, v142
	v_add_f32_e32 v143, 1.0, v143
	v_add_f32_e32 v144, 1.0, v144
	v_rcp_f32_e32 v137, v137
	v_rcp_f32_e32 v138, v138
	v_rcp_f32_e32 v139, v139
	v_rcp_f32_e32 v140, v140
	v_rcp_f32_e32 v141, v141
	v_rcp_f32_e32 v142, v142
	v_rcp_f32_e32 v143, v143
	v_rcp_f32_e32 v144, v144
	v_cvt_pk_bf16_f32 v138, v137, v138
	v_cvt_pk_bf16_f32 v139, v139, v140
	v_cvt_pk_bf16_f32 v140, v141, v142
	v_cvt_pk_bf16_f32 v141, v143, v144
	s_nop 0
	v_permlane16_swap_b32_e32 v138, v140
	v_permlane16_swap_b32_e32 v139, v141
	s_andn2_b64 exec, exec, s[36:37]
	global_store_dwordx4 v[134:135], v[138:141], off offset:256
	s_mov_b64 exec, s[36:37]
	global_store_dwordx4 v[134:135], v[138:141], off offset:256 sc1
	s_mov_b64 exec, -1
	v_mul_f32_e32 v134, 0xbfb8aa3b, v12
	v_mul_f32_e32 v135, 0xbfb8aa3b, v13
	v_mul_f32_e32 v138, 0xbfb8aa3b, v15
	v_exp_f32_e32 v138, v138
	v_mul_f32_e32 v139, 0xbfb8aa3b, v8
	v_exp_f32_e32 v139, v139
	v_mul_f32_e32 v140, 0xbfb8aa3b, v9
	v_exp_f32_e32 v140, v140
	v_add_f32_e32 v138, 1.0, v138
	v_rcp_f32_e32 v141, v138
	v_add_f32_e32 v138, 1.0, v139
	v_mul_f32_e32 v139, 0xbfb8aa3b, v10
	v_mul_f32_e32 v137, 0xbfb8aa3b, v14
	v_rcp_f32_e32 v142, v138
	v_add_f32_e32 v138, 1.0, v140
	v_exp_f32_e32 v139, v139
	v_mul_f32_e32 v140, 0xbfb8aa3b, v11
	v_exp_f32_e32 v134, v134
	v_exp_f32_e32 v135, v135
	v_exp_f32_e32 v137, v137
	v_exp_f32_e32 v140, v140
	v_rcp_f32_e32 v143, v138
	v_add_f32_e32 v138, 1.0, v139
	v_add_f32_e32 v134, 1.0, v134
	v_add_f32_e32 v135, 1.0, v135
	v_add_f32_e32 v137, 1.0, v137
	v_rcp_f32_e32 v144, v138
	v_add_f32_e32 v138, 1.0, v140
	v_add_u32_e32 v128, 0xb0, v128
	v_rcp_f32_e32 v134, v134
	v_rcp_f32_e32 v135, v135
	v_rcp_f32_e32 v137, v137
	v_rcp_f32_e32 v145, v138
	v_mad_u64_u32 v[130:131], s[40:41], v128, s71, v[130:131]
	v_lshl_add_u64 v[130:131], v[130:131], 0, s[4:5]
	v_lshl_add_u64 v[130:131], v[130:131], 0, v[132:133]
	v_cvt_pk_bf16_f32 v138, v134, v135
	v_cvt_pk_bf16_f32 v139, v137, v141
	v_cvt_pk_bf16_f32 v140, v142, v143
	v_cvt_pk_bf16_f32 v141, v144, v145
	v_add_co_u32_e32 v134, vcc, s72, v130
	v_permlane16_swap_b32_e32 v138, v140
	v_permlane16_swap_b32_e32 v139, v141
	v_addc_co_u32_e32 v135, vcc, 0, v131, vcc
	v_mul_f32_e32 v128, 0xbfb8aa3b, v4
	v_mul_f32_e32 v130, 0xbfb8aa3b, v5
	s_andn2_b64 exec, exec, s[36:37]
	global_store_dwordx4 v[134:135], v[138:141], off
	s_mov_b64 exec, s[36:37]
	global_store_dwordx4 v[134:135], v[138:141], off sc1
	s_mov_b64 exec, -1
	v_mul_f32_e32 v131, 0xbfb8aa3b, v6
	v_mul_f32_e32 v132, 0xbfb8aa3b, v7
	v_mul_f32_e32 v133, 0xbfb8aa3b, v0
	v_mul_f32_e32 v137, 0xbfb8aa3b, v1
	v_mul_f32_e32 v138, 0xbfb8aa3b, v2
	v_mul_f32_e32 v139, 0xbfb8aa3b, v3
	v_exp_f32_e32 v128, v128
	v_exp_f32_e32 v130, v130
	v_exp_f32_e32 v131, v131
	v_exp_f32_e32 v132, v132
	v_exp_f32_e32 v133, v133
	v_exp_f32_e32 v137, v137
	v_exp_f32_e32 v138, v138
	v_exp_f32_e32 v139, v139
	v_add_f32_e32 v128, 1.0, v128
	v_add_f32_e32 v130, 1.0, v130
	v_add_f32_e32 v131, 1.0, v131
	v_add_f32_e32 v132, 1.0, v132
	v_add_f32_e32 v133, 1.0, v133
	v_add_f32_e32 v137, 1.0, v137
	v_add_f32_e32 v138, 1.0, v138
	v_add_f32_e32 v139, 1.0, v139
	v_rcp_f32_e32 v128, v128
	v_rcp_f32_e32 v130, v130
	v_rcp_f32_e32 v131, v131
	v_rcp_f32_e32 v132, v132
	v_rcp_f32_e32 v133, v133
	v_rcp_f32_e32 v137, v137
	v_rcp_f32_e32 v138, v138
	v_rcp_f32_e32 v139, v139
	v_cvt_pk_bf16_f32 v130, v128, v130
	v_cvt_pk_bf16_f32 v131, v131, v132
	v_cvt_pk_bf16_f32 v132, v133, v137
	v_cvt_pk_bf16_f32 v133, v138, v139
	s_nop 0
	v_permlane16_swap_b32_e32 v130, v132
	v_permlane16_swap_b32_e32 v131, v133
	s_andn2_b64 exec, exec, s[36:37]
	global_store_dwordx4 v[134:135], v[130:133], off offset:256
	s_mov_b64 exec, s[36:37]
	global_store_dwordx4 v[134:135], v[130:133], off offset:256 sc1
	s_mov_b64 exec, -1
	s_mov_b64 s[4:5], 0
